# HGRN chunk loop: output-gate loads issued at the top of the iteration and the late vmcnt(0) before the output step dropped
# speedup vs baseline: 1.0028x; 1.0028x over previous
.LBB0_145:
	s_waitcnt vmcnt(2)
	v_pk_add_f32 v[62:63], v[110:111], 0 op_sel_hi:[1,0]
	v_mul_f32_e32 v82, 0x3fb8aa3b, v110
	v_pk_add_f32 v[68:69], v[62:63], v[112:113]
	v_mul_f32_e32 v83, 0x3fb8aa3b, v111
	v_pk_add_f32 v[70:71], v[68:69], v[120:121]
	v_exp_f32_e32 v82, v82
	v_pk_add_f32 v[72:73], v[70:71], v[126:127]
	v_exp_f32_e32 v83, v83
	v_pk_add_f32 v[74:75], v[72:73], v[130:131]
	s_waitcnt vmcnt(1)
	s_lshl_b64 s[8:9], s[92:93], 6
	v_lshl_add_u64 v[50:51], s[8:9], 0, v[132:133]
	s_movk_i32 s82, 0x600
	v_mad_u64_u32 v[48:49], s[8:9], v50, s82, v[134:135]
	v_mov_b32_e32 v50, v49
	v_mad_u64_u32 v[50:51], s[8:9], v51, s82, v[50:51]
	s_movk_i32 s89, 0x600
	v_mov_b32_e32 v49, v50
	v_mov_b32_e32 v152, 0
	v_mov_b32_e32 v156, 0
	v_mov_b32_e32 v157, 0
	s_and_saveexec_b64 s[8:9], s[26:27]
	s_cbranch_execz .LBB0_167
	global_load_dwordx2 v[156:157], v[48:49], off

.LBB0_173:
	s_or_b64 exec, exec, s[8:9]
	v_lshlrev_b32_e32 v84, 16, v158
	v_pk_add_f32 v[76:77], v[74:75], v[138:139]
	v_sub_f32_e32 v82, 1.0, v82
	v_pk_add_f32 v[60:61], v[76:77], v[144:145]
	v_sub_f32_e32 v83, 1.0, v83
	v_pk_add_f32 v[58:59], v[60:61], v[148:149]
	ds_write_b64 v169, v[58:59]
	s_waitcnt lgkmcnt(0)
	s_barrier
	ds_read2st64_b64 v[48:51], v168 offset1:1
	ds_read2st64_b64 v[52:55], v168 offset0:2 offset1:3
	v_lshlrev_b32_e32 v86, 16, v162
	v_lshlrev_b32_e32 v87, 16, v166
	s_mov_b32 s8, 0xffff0000
	s_waitcnt lgkmcnt(1)
	v_pk_add_f32 v[48:49], v[48:49], 0 op_sel_hi:[1,0]
	s_nop 0
	v_cndmask_b32_e64 v57, 0, v49, s[34:35]
	v_cndmask_b32_e64 v56, 0, v48, s[34:35]
	v_pk_add_f32 v[78:79], v[50:51], v[56:57]
	v_pk_add_f32 v[48:49], v[48:49], v[50:51]
	v_cndmask_b32_e64 v57, v57, v79, s[36:37]
	v_cndmask_b32_e64 v56, v56, v78, s[36:37]
	s_waitcnt lgkmcnt(0)
	v_pk_add_f32 v[50:51], v[52:53], v[56:57]
	v_pk_add_f32 v[52:53], v[48:49], v[52:53]
	v_cndmask_b32_e64 v57, v57, v51, s[38:39]
	v_cndmask_b32_e64 v56, v56, v50, s[38:39]
	ds_read2st64_b64 v[48:51], v168 offset0:4 offset1:5
	v_pk_add_f32 v[78:79], v[54:55], v[56:57]
	s_nop 0
	v_cndmask_b32_e64 v79, v57, v79, s[40:41]
	v_cndmask_b32_e64 v78, v56, v78, s[40:41]
	v_pk_add_f32 v[56:57], v[52:53], v[54:55]
	ds_read2st64_b64 v[52:55], v168 offset0:6 offset1:7
	s_waitcnt lgkmcnt(1)
	v_pk_add_f32 v[80:81], v[48:49], v[78:79]
	s_nop 0
	v_cndmask_b32_e64 v79, v79, v81, s[42:43]
	v_cndmask_b32_e64 v78, v78, v80, s[42:43]
	v_pk_add_f32 v[80:81], v[50:51], v[78:79]
	s_nop 0
	v_cndmask_b32_e64 v79, v79, v81, s[44:45]
	v_cndmask_b32_e64 v78, v78, v80, s[44:45]
	s_waitcnt lgkmcnt(0)
	v_pk_add_f32 v[80:81], v[52:53], v[78:79]
	s_nop 0
	v_cndmask_b32_e64 v79, v79, v81, s[46:47]
	v_cndmask_b32_e64 v78, v78, v80, s[46:47]
	v_pk_add_f32 v[80:81], v[54:55], v[78:79]
	s_nop 0
	v_cndmask_b32_e64 v79, v79, v81, s[48:49]
	v_cndmask_b32_e64 v78, v78, v80, s[48:49]
	v_pk_add_f32 v[62:63], v[62:63], v[78:79]
	v_pk_add_f32 v[60:61], v[60:61], v[78:79]
	v_pk_add_f32 v[80:81], v[62:63], v[56:57] neg_lo:[0,1] neg_hi:[0,1]
	v_pk_add_f32 v[62:63], v[56:57], v[62:63] neg_lo:[0,1] neg_hi:[0,1]
	v_min_f32_e32 v80, 0x42a00000, v80
	v_mul_f32_e32 v80, 0x3fb8aa3b, v80
	v_min_f32_e32 v81, 0x42a00000, v81
	v_min_f32_e32 v62, 0x42a00000, v62
	v_min_f32_e32 v63, 0x42a00000, v63
	v_exp_f32_e32 v80, v80
	v_mul_f32_e32 v81, 0x3fb8aa3b, v81
	v_mul_f32_e32 v62, 0x3fb8aa3b, v62
	v_mul_f32_e32 v63, 0x3fb8aa3b, v63
	v_exp_f32_e32 v81, v81
	v_exp_f32_e32 v62, v62
	v_exp_f32_e32 v63, v63
	v_mul_f32_e32 v80, v80, v84
	v_and_b32_e32 v84, 0xffff0000, v158
	v_mul_f32_e32 v81, v81, v84
	v_mul_f32_e32 v82, v82, v62
	v_mul_f32_e32 v83, v83, v63
	v_cvt_pk_bf16_f32 v62, v80, v81
	v_cvt_pk_bf16_f32 v63, v82, v83
	ds_write2st64_b32 v140, v62, v63 offset1:68
	v_pk_add_f32 v[62:63], v[68:69], v[78:79]
	v_mul_f32_e32 v80, 0x3fb8aa3b, v112
	v_pk_add_f32 v[68:69], v[62:63], v[56:57] neg_lo:[0,1] neg_hi:[0,1]
	v_pk_add_f32 v[62:63], v[56:57], v[62:63] neg_lo:[0,1] neg_hi:[0,1]
	v_min_f32_e32 v68, 0x42a00000, v68
	v_mul_f32_e32 v68, 0x3fb8aa3b, v68
	v_min_f32_e32 v69, 0x42a00000, v69
	v_min_f32_e32 v62, 0x42a00000, v62
	v_min_f32_e32 v63, 0x42a00000, v63
	v_mul_f32_e32 v81, 0x3fb8aa3b, v113
	v_exp_f32_e32 v68, v68
	v_mul_f32_e32 v69, 0x3fb8aa3b, v69
	v_mul_f32_e32 v62, 0x3fb8aa3b, v62
	v_exp_f32_e32 v80, v80
	v_exp_f32_e32 v81, v81
	v_mul_f32_e32 v63, 0x3fb8aa3b, v63
	v_exp_f32_e32 v69, v69
	v_exp_f32_e32 v62, v62
	v_exp_f32_e32 v63, v63
	v_lshlrev_b32_e32 v84, 16, v160
	v_sub_f32_e32 v80, 1.0, v80
	v_sub_f32_e32 v81, 1.0, v81
	v_mul_f32_e32 v68, v68, v84
	v_and_b32_e32 v84, 0xffff0000, v160
	v_mul_f32_e32 v69, v69, v84
	v_mul_f32_e32 v80, v80, v62
	v_mul_f32_e32 v81, v81, v63
	v_pk_add_f32 v[62:63], v[70:71], v[78:79]
	v_cvt_pk_bf16_f32 v84, v68, v69
	v_mul_f32_e32 v70, 0x3fb8aa3b, v120
	v_pk_add_f32 v[68:69], v[62:63], v[56:57] neg_lo:[0,1] neg_hi:[0,1]
	v_pk_add_f32 v[62:63], v[56:57], v[62:63] neg_lo:[0,1] neg_hi:[0,1]
	v_min_f32_e32 v68, 0x42a00000, v68
	v_mul_f32_e32 v68, 0x3fb8aa3b, v68
	v_min_f32_e32 v69, 0x42a00000, v69
	v_min_f32_e32 v62, 0x42a00000, v62
	v_exp_f32_e32 v68, v68
	v_mul_f32_e32 v69, 0x3fb8aa3b, v69
	v_mul_f32_e32 v62, 0x3fb8aa3b, v62
	v_min_f32_e32 v63, 0x42a00000, v63
	v_exp_f32_e32 v70, v70
	v_mul_f32_e32 v71, 0x3fb8aa3b, v121
	v_exp_f32_e32 v69, v69
	v_exp_f32_e32 v62, v62
	v_exp_f32_e32 v71, v71
	v_mul_f32_e32 v63, 0x3fb8aa3b, v63
	v_exp_f32_e32 v63, v63
	v_sub_f32_e32 v70, 1.0, v70
	v_mul_f32_e32 v68, v68, v86
	v_and_b32_e32 v86, 0xffff0000, v162
	v_sub_f32_e32 v71, 1.0, v71
	v_mul_f32_e32 v69, v69, v86
	v_mul_f32_e32 v70, v70, v62
	v_cvt_pk_bf16_f32 v62, v68, v69
	v_mul_f32_e32 v71, v71, v63
	ds_write2_b32 v142, v84, v62 offset1:68
	v_cvt_pk_bf16_f32 v62, v70, v71
	v_add_u32_e32 v84, 0x4400, v142
	v_cvt_pk_bf16_f32 v85, v80, v81
	ds_write2_b32 v84, v85, v62 offset1:68
	v_pk_add_f32 v[62:63], v[72:73], v[78:79]
	v_mul_f32_e32 v72, 0x3fb8aa3b, v126
	v_pk_add_f32 v[68:69], v[62:63], v[56:57] neg_lo:[0,1] neg_hi:[0,1]
	v_pk_add_f32 v[62:63], v[56:57], v[62:63] neg_lo:[0,1] neg_hi:[0,1]
	v_min_f32_e32 v68, 0x42a00000, v68
	v_mul_f32_e32 v68, 0x3fb8aa3b, v68
	v_min_f32_e32 v69, 0x42a00000, v69
	v_min_f32_e32 v62, 0x42a00000, v62
	v_min_f32_e32 v63, 0x42a00000, v63
	v_mul_f32_e32 v73, 0x3fb8aa3b, v127
	v_exp_f32_e32 v68, v68
	v_mul_f32_e32 v69, 0x3fb8aa3b, v69
	v_mul_f32_e32 v62, 0x3fb8aa3b, v62
	v_exp_f32_e32 v72, v72
	v_exp_f32_e32 v73, v73
	v_mul_f32_e32 v63, 0x3fb8aa3b, v63
	v_exp_f32_e32 v69, v69
	v_exp_f32_e32 v62, v62
	v_exp_f32_e32 v63, v63
	v_lshlrev_b32_e32 v85, 16, v164
	v_sub_f32_e32 v72, 1.0, v72
	v_sub_f32_e32 v73, 1.0, v73
	v_mul_f32_e32 v68, v68, v85
	v_and_b32_e32 v85, 0xffff0000, v164
	v_mul_f32_e32 v69, v69, v85
	v_mul_f32_e32 v85, v72, v62
	v_mul_f32_e32 v73, v73, v63
	v_pk_add_f32 v[62:63], v[74:75], v[78:79]
	v_cvt_pk_bf16_f32 v72, v68, v69
	v_mul_f32_e32 v74, 0x3fb8aa3b, v130
	v_pk_add_f32 v[68:69], v[62:63], v[56:57] neg_lo:[0,1] neg_hi:[0,1]
	v_pk_add_f32 v[62:63], v[56:57], v[62:63] neg_lo:[0,1] neg_hi:[0,1]
	v_min_f32_e32 v68, 0x42a00000, v68
	v_mul_f32_e32 v68, 0x3fb8aa3b, v68
	v_min_f32_e32 v69, 0x42a00000, v69
	v_min_f32_e32 v62, 0x42a00000, v62
	v_exp_f32_e32 v68, v68
	v_mul_f32_e32 v69, 0x3fb8aa3b, v69
	v_mul_f32_e32 v62, 0x3fb8aa3b, v62
	v_min_f32_e32 v63, 0x42a00000, v63
	v_exp_f32_e32 v74, v74
	v_mul_f32_e32 v75, 0x3fb8aa3b, v131
	v_exp_f32_e32 v69, v69
	v_exp_f32_e32 v62, v62
	v_exp_f32_e32 v75, v75
	v_mul_f32_e32 v63, 0x3fb8aa3b, v63
	v_exp_f32_e32 v63, v63
	v_sub_f32_e32 v74, 1.0, v74
	v_mul_f32_e32 v68, v68, v87
	v_and_b32_e32 v87, 0xffff0000, v166
	v_sub_f32_e32 v75, 1.0, v75
	v_mul_f32_e32 v69, v69, v87
	v_mul_f32_e32 v74, v74, v62
	v_cvt_pk_bf16_f32 v62, v68, v69
	v_mul_f32_e32 v75, v75, v63
	ds_write2_b32 v142, v72, v62 offset0:136 offset1:204
	v_cvt_pk_bf16_f32 v62, v74, v75
	v_cvt_pk_bf16_f32 v86, v85, v73
	ds_write2_b32 v84, v86, v62 offset0:136 offset1:204
	v_pk_add_f32 v[62:63], v[76:77], v[78:79]
	v_mul_f32_e32 v72, 0x3fb8aa3b, v138
	v_pk_add_f32 v[68:69], v[62:63], v[56:57] neg_lo:[0,1] neg_hi:[0,1]
	v_pk_add_f32 v[62:63], v[56:57], v[62:63] neg_lo:[0,1] neg_hi:[0,1]
	v_mul_f32_e32 v76, 0x3fb8aa3b, v139
	v_min_f32_e32 v62, 0x42a00000, v62
	v_min_f32_e32 v63, 0x42a00000, v63
	v_mul_f32_e32 v62, 0x3fb8aa3b, v62
	v_exp_f32_e32 v72, v72
	v_exp_f32_e32 v76, v76
	v_mul_f32_e32 v63, 0x3fb8aa3b, v63
	v_exp_f32_e32 v62, v62
	v_exp_f32_e32 v63, v63
	v_min_f32_e32 v68, 0x42a00000, v68
	v_sub_f32_e32 v72, 1.0, v72
	v_sub_f32_e32 v76, 1.0, v76
	v_mul_f32_e32 v68, 0x3fb8aa3b, v68
	v_min_f32_e32 v69, 0x42a00000, v69
	v_mul_f32_e32 v84, v72, v62
	v_mul_f32_e32 v86, v76, v63
	v_pk_add_f32 v[62:63], v[60:61], v[56:57] neg_lo:[0,1] neg_hi:[0,1]
	v_exp_f32_e32 v68, v68
	v_mul_f32_e32 v69, 0x3fb8aa3b, v69
	v_min_f32_e32 v62, 0x42a00000, v62
	v_pk_add_f32 v[60:61], v[56:57], v[60:61] neg_lo:[0,1] neg_hi:[0,1]
	v_exp_f32_e32 v69, v69
	v_mul_f32_e32 v62, 0x3fb8aa3b, v62
	v_min_f32_e32 v63, 0x42a00000, v63
	v_min_f32_e32 v60, 0x42a00000, v60
	v_min_f32_e32 v61, 0x42a00000, v61
	v_mul_f32_e32 v72, 0x3fb8aa3b, v144
	v_mul_f32_e32 v76, 0x3fb8aa3b, v145
	v_exp_f32_e32 v62, v62
	v_mul_f32_e32 v63, 0x3fb8aa3b, v63
	v_mul_f32_e32 v60, 0x3fb8aa3b, v60
	v_exp_f32_e32 v72, v72
	v_exp_f32_e32 v76, v76
	v_mul_f32_e32 v61, 0x3fb8aa3b, v61
	v_lshlrev_b32_e32 v77, 16, v176
	v_exp_f32_e32 v63, v63
	v_exp_f32_e32 v60, v60
	v_exp_f32_e32 v61, v61
	v_mul_f32_e32 v68, v68, v77
	v_and_b32_e32 v77, 0xffff0000, v176
	v_mul_f32_e32 v69, v69, v77
	v_lshlrev_b32_e32 v77, 16, v182
	v_sub_f32_e32 v72, 1.0, v72
	v_sub_f32_e32 v76, 1.0, v76
	v_mul_f32_e32 v62, v62, v77
	v_and_b32_e32 v77, 0xffff0000, v182
	v_mul_f32_e32 v63, v63, v77
	v_mul_f32_e32 v87, v72, v60
	v_mul_f32_e32 v88, v76, v61
	v_cvt_pk_bf16_f32 v60, v62, v63
	v_add_u32_e32 v61, 0x400, v142
	v_cvt_pk_bf16_f32 v68, v68, v69
	ds_write2_b32 v61, v68, v60 offset0:16 offset1:84
	v_cvt_pk_bf16_f32 v60, v87, v88
	v_add_u32_e32 v61, 0x4800, v142
	v_pk_add_f32 v[58:59], v[58:59], v[78:79]
	v_cvt_pk_bf16_f32 v69, v84, v86
	ds_write2_b32 v61, v69, v60 offset0:16 offset1:84
	v_pk_add_f32 v[60:61], v[58:59], v[56:57] neg_lo:[0,1] neg_hi:[0,1]
	v_pk_add_f32 v[58:59], v[56:57], v[58:59] neg_lo:[0,1] neg_hi:[0,1]
	v_min_f32_e32 v60, 0x42a00000, v60
	v_mul_f32_e32 v60, 0x3fb8aa3b, v60
	v_min_f32_e32 v61, 0x42a00000, v61
	v_min_f32_e32 v58, 0x42a00000, v58
	v_mul_f32_e32 v62, 0x3fb8aa3b, v148
	v_exp_f32_e32 v60, v60
	v_mul_f32_e32 v61, 0x3fb8aa3b, v61
	v_mul_f32_e32 v58, 0x3fb8aa3b, v58
	v_exp_f32_e32 v62, v62
	v_exp_f32_e32 v61, v61
	v_exp_f32_e32 v58, v58
	v_min_f32_e32 v59, 0x42a00000, v59
	v_mul_f32_e32 v63, 0x3fb8aa3b, v149
	v_exp_f32_e32 v63, v63
	v_mul_f32_e32 v59, 0x3fb8aa3b, v59
	v_exp_f32_e32 v59, v59
	v_lshlrev_b32_e32 v68, 16, v1
	v_sub_f32_e32 v62, 1.0, v62
	v_mul_f32_e32 v60, v60, v68
	v_and_b32_e32 v68, 0xffff0000, v1
	v_mul_f32_e32 v61, v61, v68
	v_mul_f32_e32 v62, v62, v58
	v_cvt_pk_bf16_f32 v58, v60, v61
	s_waitcnt vmcnt(0)
	v_and_b32_e32 v60, 0xffff, v163
	v_sub_f32_e32 v63, 1.0, v63
	v_cvt_pk_bf16_f32 v69, v71, v73
	v_lshl_or_b32 v73, v161, 16, v60
	v_lshrrev_b32_e32 v60, 16, v163
	v_and_b32_e32 v61, 0xffff, v167
	v_mul_f32_e32 v63, v63, v59
	v_and_b32_e32 v59, 0xffff, v159
	v_and_or_b32 v77, v161, s8, v60
	v_cvt_pk_bf16_f32 v60, v74, v84
	v_lshl_or_b32 v74, v165, 16, v61
	v_lshrrev_b32_e32 v61, 16, v167
	ds_write_b32 v142, v58 offset:1632
	v_cvt_pk_bf16_f32 v58, v62, v63
	v_lshl_or_b32 v72, v103, 16, v59
	v_lshrrev_b32_e32 v59, 16, v159
	v_and_or_b32 v78, v165, s8, v61
	v_cvt_pk_bf16_f32 v61, v87, v62
	v_and_b32_e32 v62, 0xffff, v183
	ds_write_b32 v142, v58 offset:19040
	v_cvt_pk_bf16_f32 v58, v82, v80
	v_and_or_b32 v76, v103, s8, v59
	v_cvt_pk_bf16_f32 v59, v70, v85
	v_cvt_pk_bf16_f32 v70, v75, v86
	v_lshl_or_b32 v75, v209, 16, v62
	v_lshrrev_b32_e32 v62, 16, v183
	v_cvt_pk_bf16_f32 v68, v83, v81
	v_cvt_pk_bf16_f32 v71, v88, v63
	v_and_or_b32 v79, v209, s8, v62
	ds_write_b128 v170, v[58:61] offset:34816
	ds_write_b128 v170, v[68:71] offset:34960
	ds_write_b128 v170, v[72:75] offset:53248
	ds_write_b128 v170, v[76:79] offset:53392
	s_and_saveexec_b64 s[8:9], s[24:25]
	s_cbranch_execz .LBB0_147
	v_pk_add_f32 v[48:49], v[56:57], v[48:49]
	s_nop 0
	v_pk_add_f32 v[48:49], v[48:49], v[50:51]
	v_mul_f32_e32 v50, 0x3fb8aa3b, v56
	v_pk_add_f32 v[48:49], v[48:49], v[52:53]
	v_mul_f32_e32 v51, 0x3fb8aa3b, v57
	v_pk_add_f32 v[48:49], v[48:49], v[54:55]
	v_exp_f32_e32 v50, v50
	v_pk_add_f32 v[48:49], v[48:49], v[56:57] neg_lo:[0,1] neg_hi:[0,1]
	v_exp_f32_e32 v51, v51
	v_mul_f32_e32 v48, 0x3fb8aa3b, v48
	v_mul_f32_e32 v49, 0x3fb8aa3b, v49
	v_exp_f32_e32 v48, v48
	v_exp_f32_e32 v49, v49
	ds_write_b64 v171, v[50:51]
	ds_write_b64 v172, v[48:49]

.LBB0_165:
	s_movk_i32 s89, 0x600
	s_waitcnt lgkmcnt(0)
	s_barrier
	ds_read_b128 v[48:51], v143
	ds_read_b128 v[222:225], v143 offset:32
	ds_read_b128 v[226:229], v143 offset:64
	ds_read_b128 v[230:233], v143 offset:96
	ds_read_b128 v[234:237], v143 offset:128
	s_waitcnt lgkmcnt(4)
	v_pk_mul_f32 v[16:17], v[16:17], v[48:49]
	v_pk_mul_f32 v[18:19], v[18:19], v[50:51]
	v_cvt_pk_bf16_f32 v48, v16, v17
	s_nop 0
	v_cvt_pk_bf16_f32 v49, v18, v19
	ds_write_b64 v181, v[48:49]
	ds_read_b128 v[48:51], v143 offset:160
	s_waitcnt lgkmcnt(5)
	v_pk_mul_f32 v[20:21], v[20:21], v[222:223]
	v_pk_mul_f32 v[22:23], v[22:23], v[224:225]
	v_cvt_pk_bf16_f32 v222, v20, v21
	s_nop 0
	v_cvt_pk_bf16_f32 v223, v22, v23
	ds_write_b64 v181, v[222:223] offset:16
	ds_read_b128 v[222:225], v143 offset:192
	s_waitcnt lgkmcnt(6)
	v_pk_mul_f32 v[24:25], v[24:25], v[226:227]
	v_pk_mul_f32 v[26:27], v[26:27], v[228:229]
	v_cvt_pk_bf16_f32 v226, v24, v25
	s_nop 0
	v_cvt_pk_bf16_f32 v227, v26, v27
	ds_write_b64 v181, v[226:227] offset:32
	ds_read_b128 v[226:229], v143 offset:224
	s_waitcnt lgkmcnt(7)
	v_pk_mul_f32 v[28:29], v[28:29], v[230:231]
	v_pk_mul_f32 v[30:31], v[30:31], v[232:233]
	v_cvt_pk_bf16_f32 v230, v28, v29
	s_nop 0
	v_cvt_pk_bf16_f32 v231, v30, v31
	ds_write_b64 v181, v[230:231] offset:48
	s_waitcnt lgkmcnt(7)
	v_pk_mul_f32 v[32:33], v[32:33], v[234:235]
	v_pk_mul_f32 v[34:35], v[34:35], v[236:237]
	v_cvt_pk_bf16_f32 v234, v32, v33
	s_nop 0
	v_cvt_pk_bf16_f32 v235, v34, v35
	ds_write_b64 v181, v[234:235] offset:64
	s_waitcnt lgkmcnt(6)
	v_pk_mul_f32 v[36:37], v[36:37], v[48:49]
	v_pk_mul_f32 v[38:39], v[38:39], v[50:51]
	v_cvt_pk_bf16_f32 v48, v36, v37
	s_nop 0
	v_cvt_pk_bf16_f32 v49, v38, v39
	ds_write_b64 v181, v[48:49] offset:80
	s_waitcnt lgkmcnt(5)
	v_pk_mul_f32 v[40:41], v[40:41], v[222:223]
	v_pk_mul_f32 v[42:43], v[42:43], v[224:225]
	v_cvt_pk_bf16_f32 v222, v40, v41
	s_nop 0
	v_cvt_pk_bf16_f32 v223, v42, v43
	ds_write_b64 v181, v[222:223] offset:96
	s_waitcnt lgkmcnt(4)
	v_pk_mul_f32 v[44:45], v[44:45], v[226:227]
	v_pk_mul_f32 v[46:47], v[46:47], v[228:229]
	v_cvt_pk_bf16_f32 v226, v44, v45
	s_nop 0
	v_cvt_pk_bf16_f32 v227, v46, v47
	ds_write_b64 v181, v[226:227] offset:112
	s_waitcnt lgkmcnt(0)
	s_barrier
	s_and_saveexec_b64 s[82:83], s[28:29]
	s_cbranch_execz .LBB0_175
	ds_read_b128 v[48:51], v173 offset:17408
	ds_read_b128 v[52:55], v174
	ds_read_b128 v[68:71], v173 offset:17440
	ds_read_b128 v[72:75], v174 offset:32
	ds_read_b128 v[76:79], v173 offset:17472
	ds_read_b128 v[80:83], v174 offset:64
	ds_read_b128 v[84:87], v173 offset:17504
	ds_read_b128 v[88:91], v174 offset:96
	ds_read_b128 v[92:95], v173 offset:17536
	ds_read_b128 v[96:99], v174 offset:128
	ds_read_b128 v[222:225], v173 offset:17568
	ds_read_b128 v[226:229], v174 offset:160
	ds_read_b128 v[230:233], v173 offset:17600
	ds_read_b128 v[234:237], v174 offset:192
	s_waitcnt lgkmcnt(12)
	v_mfma_f32_32x32x16_bf16 v[48:63], v[48:51], v[52:55], 0
	s_waitcnt lgkmcnt(10)
	v_mfma_f32_32x32x16_bf16 v[48:63], v[68:71], v[72:75], v[48:63]
	ds_read_b128 v[68:71], v173 offset:17632
	ds_read_b128 v[72:75], v174 offset:224
	s_waitcnt lgkmcnt(10)
	v_mfma_f32_32x32x16_bf16 v[48:63], v[76:79], v[80:83], v[48:63]
	s_waitcnt lgkmcnt(8)
	v_mfma_f32_32x32x16_bf16 v[48:63], v[84:87], v[88:91], v[48:63]
	s_waitcnt lgkmcnt(6)
	v_mfma_f32_32x32x16_bf16 v[48:63], v[92:95], v[96:99], v[48:63]
	s_waitcnt lgkmcnt(4)
	v_mfma_f32_32x32x16_bf16 v[48:63], v[222:225], v[226:229], v[48:63]
	s_waitcnt lgkmcnt(2)
	v_mfma_f32_32x32x16_bf16 v[48:63], v[230:233], v[234:237], v[48:63]
	s_waitcnt lgkmcnt(0)
	v_mfma_f32_32x32x16_bf16 v[48:63], v[68:71], v[72:75], v[48:63]
	s_nop 11
	v_cndmask_b32_e64 v48, v48, 0, s[50:51]
	v_cndmask_b32_e64 v49, 0, v49, s[52:53]
	v_cndmask_b32_e64 v50, v50, 0, s[54:55]
	v_cndmask_b32_e64 v51, v51, 0, s[56:57]
	v_cndmask_b32_e64 v52, v52, 0, s[58:59]
	v_cndmask_b32_e64 v53, v53, 0, s[60:61]
	v_cndmask_b32_e64 v54, v54, 0, s[62:63]
	v_cndmask_b32_e64 v55, v55, 0, s[64:65]
	v_cvt_pk_bf16_f32 v48, v48, v49
	v_cvt_pk_bf16_f32 v49, v50, v51
	v_cvt_pk_bf16_f32 v50, v52, v53
	v_cvt_pk_bf16_f32 v51, v54, v55
	v_cndmask_b32_e64 v56, v56, 0, s[66:67]
	v_cndmask_b32_e64 v57, v57, 0, s[68:69]
	v_cndmask_b32_e64 v58, v58, 0, s[70:71]
	v_cndmask_b32_e64 v59, v59, 0, s[72:73]
	v_cndmask_b32_e64 v60, v60, 0, s[74:75]
	v_cndmask_b32_e64 v61, v61, 0, s[76:77]
	v_cndmask_b32_e64 v62, v62, 0, s[78:79]
	v_cndmask_b32_e64 v63, v63, 0, s[80:81]
	v_cvt_pk_bf16_f32 v52, v56, v57
	v_cvt_pk_bf16_f32 v53, v58, v59
	v_cvt_pk_bf16_f32 v54, v60, v61
	v_cvt_pk_bf16_f32 v55, v62, v63
	ds_write2_b64 v204, v[48:49], v[50:51] offset1:2
	ds_write2_b64 v204, v[52:53], v[54:55] offset0:4 offset1:6

.LBB0_179:
	s_or_b64 exec, exec, s[8:9]
	s_waitcnt lgkmcnt(0)
	s_barrier
	s_and_saveexec_b64 s[82:83], s[26:27]
	s_cbranch_execz .LBB0_144
	ds_read2st64_b32 v[210:211], v180 offset1:1
	v_lshlrev_b32_e32 v213, 16, v156
	v_and_b32_e32 v156, 0xffff0000, v156
	s_lshl_b64 s[8:9], s[92:93], 17
	s_waitcnt lgkmcnt(0)
	v_add_f32_e32 v212, v210, v211
	ds_read2st64_b32 v[210:211], v180 offset0:2 offset1:3
	s_waitcnt lgkmcnt(0)
	v_add_f32_e32 v210, v212, v210
	v_add_f32_e32 v210, v210, v211
	v_fmamk_f32 v210, v210, 0x3c000000, v188
	v_rsq_f32_e32 v212, v210
	v_lshl_add_u64 v[210:211], v[146:147], 0, s[8:9]
	v_mul_f32_e32 v48, v48, v212
	v_mul_f32_e32 v49, v49, v212
	v_mul_f32_e32 v48, v2, v48
	v_mul_f32_e32 v49, v3, v49
	v_mul_f32_e32 v50, v50, v212
	v_mul_f32_e32 v48, v48, v213
	v_mul_f32_e32 v49, v49, v156
	v_mul_f32_e32 v50, v4, v50
	v_lshlrev_b32_e32 v156, 16, v157
	v_mul_f32_e32 v51, v51, v212
	v_mul_f32_e32 v50, v50, v156
	v_mul_f32_e32 v51, v5, v51
	v_and_b32_e32 v156, 0xffff0000, v157
	v_cvt_pk_bf16_f32 v48, v48, v49
	v_mul_f32_e32 v51, v51, v156
	v_cvt_pk_bf16_f32 v49, v50, v51
	global_store_dwordx2 v[210:211], v[48:49], off
	v_mul_f32_e32 v48, v52, v212
	v_mul_f32_e32 v48, v6, v48
	v_lshlrev_b32_e32 v49, 16, v152
	v_mul_f32_e32 v48, v48, v49
	v_mul_f32_e32 v49, v53, v212
	v_mul_f32_e32 v49, v7, v49
	v_and_b32_e32 v50, 0xffff0000, v152
	v_mul_f32_e32 v49, v49, v50
	v_mul_f32_e32 v50, v54, v212
	v_mul_f32_e32 v50, v8, v50
	v_lshlrev_b32_e32 v51, 16, v153
	v_mul_f32_e32 v50, v50, v51
	v_mul_f32_e32 v51, v55, v212
	v_mul_f32_e32 v51, v9, v51
	v_and_b32_e32 v52, 0xffff0000, v153
	v_cvt_pk_bf16_f32 v48, v48, v49
	v_mul_f32_e32 v51, v51, v52
	v_cvt_pk_bf16_f32 v49, v50, v51
	global_store_dwordx2 v[210:211], v[48:49], off offset:16
	v_mul_f32_e32 v48, v56, v212
	v_mul_f32_e32 v48, v10, v48
	v_lshlrev_b32_e32 v49, 16, v154
	v_mul_f32_e32 v48, v48, v49
	v_mul_f32_e32 v49, v57, v212
	v_mul_f32_e32 v49, v11, v49
	v_and_b32_e32 v50, 0xffff0000, v154
	v_mul_f32_e32 v49, v49, v50
	v_mul_f32_e32 v50, v58, v212
	v_mul_f32_e32 v50, v12, v50
	v_lshlrev_b32_e32 v51, 16, v155
	v_mul_f32_e32 v50, v50, v51
	v_mul_f32_e32 v51, v59, v212
	v_mul_f32_e32 v51, v13, v51
	v_and_b32_e32 v52, 0xffff0000, v155
	v_cvt_pk_bf16_f32 v48, v48, v49
	v_mul_f32_e32 v51, v51, v52
	v_cvt_pk_bf16_f32 v49, v50, v51
	global_store_dwordx2 v[210:211], v[48:49], off offset:32
	v_mul_f32_e32 v48, v60, v212
	v_mul_f32_e32 v48, v64, v48
	v_lshlrev_b32_e32 v49, 16, v150
	v_mul_f32_e32 v48, v48, v49
	v_mul_f32_e32 v49, v61, v212
	v_mul_f32_e32 v49, v65, v49
	v_and_b32_e32 v50, 0xffff0000, v150
	v_mul_f32_e32 v49, v49, v50
	v_mul_f32_e32 v50, v62, v212
	v_mul_f32_e32 v50, v66, v50
	v_lshlrev_b32_e32 v51, 16, v151
	v_mul_f32_e32 v50, v50, v51
	v_mul_f32_e32 v51, v63, v212
	v_mul_f32_e32 v51, v67, v51
	v_and_b32_e32 v52, 0xffff0000, v151
	v_mul_f32_e32 v51, v51, v52
	v_cvt_pk_bf16_f32 v48, v48, v49
	v_cvt_pk_bf16_f32 v49, v50, v51
	global_store_dwordx2 v[210:211], v[48:49], off offset:48
	s_branch .LBB0_144
